# defer up/down weight conversion of layers 1,3 from prologue into compress phase idle workgroups
# speedup vs baseline: 1.0027x; 1.0027x over previous
; __device__ __forceinline__ const float* arg_in(int i) { return *(const float* const __attribute__((address_space(4)))*)(karg_base() + 8 * i); }
; __device__ __forceinline__ unsigned char* arg_ws() { return *(unsigned char* const __attribute__((address_space(4)))*)(karg_base() + 8 * 20); }
; __device__ __forceinline__ void prologue_phase(LAS unsigned char* lds) {
;     ...
;     for (int mi = 0; mi < 24; ++mi) {
;         unsigned char* ws = arg_ws();
;         const float* W; int K, N; bf16_t* WT; const float* g = nullptr;
;         if (mi < 4) { W = arg_in(17) + (size_t)mi * DM * DFF; K = DM; N = DFF; WT = (bf16_t*)(ws + WS_WUP) + (size_t)mi * DFF * DM; g = arg_in(3) + mi * DM; }
;         else if (mi < 8) { const int L = mi - 4; W = arg_in(18) + (size_t)L * DFF * DM; K = DFF; N = DM; WT = (bf16_t*)(ws + WS_WDN) + (size_t)L * DM * DFF; }
.LBB0_8:
	s_cmp_gt_u32 s8, 7
	s_cbranch_scc1 .Ldcv_keep
	s_bitcmp1_b32 s8, 0
	s_cbranch_scc1 .LBB0_7

; #define LAS __attribute__((address_space(3)))
; __device__ __forceinline__ const float* arg_in(int i) { return *(const float* const __attribute__((address_space(4)))*)(karg_base() + 8 * i); }
; __device__ __forceinline__ void tr_load(float (&v)[32], const float* W, int K, int N, int item, int lane) {
;     const int nblk = (N + 31) / 32, kb = item / nblk, nb = item - kb * nblk, k0 = 64 * kb, n0 = 32 * nb;
;     const int nn = n0 + (lane & 31); const bool ok = nn < N;
;     const float* p = W + (size_t)(k0 + (lane >> 5)) * N + (ok ? nn : 0);
; #pragma unroll
;     for (int i = 0; i < 32; ++i) { const float x = __builtin_nontemporal_load(p + (size_t)(2 * i) * N); v[i] = ok ? x : 0.f; }
; }
; __device__ __forceinline__ void tr_put(const float (&v)[32], LAS float* scr, int lane) {
; #pragma unroll
;     for (int i = 0; i < 32; ++i) scr[(2 * i + (lane >> 5)) * 33 + (lane & 31)] = v[i];
; __device__ __forceinline__ void prologue_phase(LAS unsigned char* lds) {
;     ...
;         if (mi < 4) { W = arg_in(17) + (size_t)mi * DM * DFF; K = DM; N = DFF; WT = (bf16_t*)(ws + WS_WUP) + (size_t)mi * DFF * DM; g = arg_in(3) + mi * DM; }
;         else if (mi < 8) { const int L = mi - 4; W = arg_in(18) + (size_t)L * DFF * DM; K = DFF; N = DM; WT = (bf16_t*)(ws + WS_WDN) + (size_t)L * DM * DFF; }
.Ldcv_entry:
	v_readlane_b32 s16, v255, 7
	v_and_b32_e32 v34, 31, v202
	v_bfe_u32 v35, v202, 5, 1
	v_lshrrev_b32_e32 v0, 6, v202
	s_lshl_b32 s16, s16, 1
	s_add_i32 s16, s16, 1
	v_readfirstlane_b32 s19, v0
	s_sub_i32 s31, s61, 0x80
	s_lshl_b32 s31, s31, 3
	s_add_i32 s19, s31, s19
	v_lshlrev_b32_e32 v0, 14, v0
	v_mul_u32_u24_e32 v36, 33, v35
	v_add_u32_e32 v36, v36, v34
	v_lshl_add_u32 v36, v36, 2, v0
	v_and_b32_e32 v42, 7, v202
	v_bfe_u32 v43, v202, 3, 3
	v_mul_u32_u24_e32 v37, 0x108, v42
	v_add_u32_e32 v37, v37, v43
	v_lshl_add_u32 v37, v37, 2, v0
	s_load_dwordx2 s[28:29], s[62:63], 0xa0
	s_mov_b32 s17, 0
.Ldcv_matrix:
	s_cmp_eq_u32 s17, 0
	s_cbranch_scc0 .Ldcv_dn
	s_load_dwordx2 s[20:21], s[62:63], 0x88
	s_load_dwordx2 s[24:25], s[62:63], 0x18
	s_mov_b32 s36, 8
	s_mov_b32 s37, 0x8000
	s_mov_b32 s38, 0x1000
	s_mov_b32 s39, 0x1000000
	s_branch .Ldcv_setup
.Ldcv_dn:
	s_load_dwordx2 s[20:21], s[62:63], 0x90
	s_mov_b32 s36, 6
	s_mov_b32 s37, 0x2000
	s_mov_b32 s38, 0x4000
	s_mov_b32 s39, 0x9000000
	v_mov_b32_e32 v222, 1.0
	v_mov_b32_e32 v223, 1.0
	v_mov_b32_e32 v224, 1.0
	v_mov_b32_e32 v225, 1.0
	v_mov_b32_e32 v226, 1.0
	v_mov_b32_e32 v227, 1.0
	v_mov_b32_e32 v228, 1.0
	v_mov_b32_e32 v229, 1.0
.Ldcv_setup:
	s_waitcnt lgkmcnt(0)
	s_lshl_b32 s31, s16, 26
	s_add_u32 s20, s20, s31
	s_addc_u32 s21, s21, 0
	s_lshl_b32 s31, s16, 25
	s_add_u32 s22, s28, s31
	s_addc_u32 s23, s29, 0
	s_add_u32 s22, s22, s39
	s_addc_u32 s23, s23, 0
	s_lshl_b32 s31, s16, 13
	s_add_u32 s24, s24, s31
	s_addc_u32 s25, s25, 0
	s_lshl_b32 s44, s37, 1
	s_lshl_b32 s45, s38, 3
	s_mov_b32 s30, s19
.Ldcv_item:
	s_lshr_b32 s34, s30, s36
	s_lshl_b32 s35, s34, s36
	s_sub_i32 s35, s30, s35
	s_lshl_b32 s42, s34, 6
	s_lshl_b32 s43, s35, 5
	s_cmp_eq_u32 s17, 0
	s_cbranch_scc0 .Ldcv_nogain
	v_lshl_add_u32 v40, v42, 3, s42
	v_lshlrev_b32_e32 v40, 2, v40
	global_load_dwordx4 v[222:225], v40, s[24:25]
	global_load_dwordx4 v[226:229], v40, s[24:25] offset:16
.Ldcv_nogain:
	v_add_u32_e32 v38, s42, v35
	v_mul_lo_u32 v38, v38, s37
	v_add_u32_e32 v39, s43, v34
	v_lshl_add_u32 v38, v39, 2, v38
	global_load_dword v98, v38, s[20:21] nt
	v_add_u32_e32 v38, s44, v38
	global_load_dword v99, v38, s[20:21] nt
	v_add_u32_e32 v38, s44, v38
	global_load_dword v100, v38, s[20:21] nt
	v_add_u32_e32 v38, s44, v38
	global_load_dword v101, v38, s[20:21] nt
	v_add_u32_e32 v38, s44, v38
	global_load_dword v102, v38, s[20:21] nt
	v_add_u32_e32 v38, s44, v38
	global_load_dword v103, v38, s[20:21] nt
	v_add_u32_e32 v38, s44, v38
	global_load_dword v104, v38, s[20:21] nt
	v_add_u32_e32 v38, s44, v38
	global_load_dword v105, v38, s[20:21] nt
	v_add_u32_e32 v38, s44, v38
	global_load_dword v106, v38, s[20:21] nt
	v_add_u32_e32 v38, s44, v38
	global_load_dword v107, v38, s[20:21] nt
	v_add_u32_e32 v38, s44, v38
	global_load_dword v108, v38, s[20:21] nt
	v_add_u32_e32 v38, s44, v38
	global_load_dword v109, v38, s[20:21] nt
	v_add_u32_e32 v38, s44, v38
	global_load_dword v110, v38, s[20:21] nt
	v_add_u32_e32 v38, s44, v38
	global_load_dword v111, v38, s[20:21] nt
	v_add_u32_e32 v38, s44, v38
	global_load_dword v112, v38, s[20:21] nt
	v_add_u32_e32 v38, s44, v38
	global_load_dword v113, v38, s[20:21] nt
	v_add_u32_e32 v38, s44, v38
	global_load_dword v114, v38, s[20:21] nt
	v_add_u32_e32 v38, s44, v38
	global_load_dword v115, v38, s[20:21] nt
	v_add_u32_e32 v38, s44, v38
	global_load_dword v116, v38, s[20:21] nt
	v_add_u32_e32 v38, s44, v38
	global_load_dword v117, v38, s[20:21] nt
	v_add_u32_e32 v38, s44, v38
	global_load_dword v118, v38, s[20:21] nt
	v_add_u32_e32 v38, s44, v38
	global_load_dword v119, v38, s[20:21] nt
	v_add_u32_e32 v38, s44, v38
	global_load_dword v120, v38, s[20:21] nt
	v_add_u32_e32 v38, s44, v38
	global_load_dword v121, v38, s[20:21] nt
	v_add_u32_e32 v38, s44, v38
	global_load_dword v204, v38, s[20:21] nt
	v_add_u32_e32 v38, s44, v38
	global_load_dword v205, v38, s[20:21] nt
	v_add_u32_e32 v38, s44, v38
	global_load_dword v206, v38, s[20:21] nt
	v_add_u32_e32 v38, s44, v38
	global_load_dword v207, v38, s[20:21] nt
	v_add_u32_e32 v38, s44, v38
	global_load_dword v208, v38, s[20:21] nt
	v_add_u32_e32 v38, s44, v38
	global_load_dword v209, v38, s[20:21] nt
	v_add_u32_e32 v38, s44, v38
	global_load_dword v210, v38, s[20:21] nt
	v_add_u32_e32 v38, s44, v38
	global_load_dword v211, v38, s[20:21] nt
	v_add_u32_e32 v40, s43, v43
	v_mul_lo_u32 v40, v40, s38
	v_lshl_add_u32 v41, v42, 3, s42
	v_lshl_add_u32 v40, v41, 1, v40
	s_waitcnt vmcnt(31)
	ds_write_b32 v36, v98
	s_waitcnt vmcnt(30)
	ds_write_b32 v36, v99 offset:264
	s_waitcnt vmcnt(29)
	ds_write_b32 v36, v100 offset:528
	s_waitcnt vmcnt(28)
; #define LAS __attribute__((address_space(3)))
; __device__ __forceinline__ void tr_put(const float (&v)[32], LAS float* scr, int lane) {
; #pragma unroll
;     for (int i = 0; i < 32; ++i) scr[(2 * i + (lane >> 5)) * 33 + (lane & 31)] = v[i];
; }
; __device__ __forceinline__ void tr_put_gain(const float (&v)[32], LAS float* scr, int lane, const LAS float* gk) {
; #pragma unroll
;     for (int i = 0; i < 32; ++i) scr[(2 * i + (lane >> 5)) * 33 + (lane & 31)] = v[i] * gk[2 * i + (lane >> 5)];
; }
; __device__ __forceinline__ void tr_store(bf16_t* WT, int K, int N, LAS float* scr, int item, int lane) {
;     const int nblk = (N + 31) / 32, kb = item / nblk, nb = item - kb * nblk, k0 = 64 * kb, n0 = 32 * nb;
;     const int c = lane & 7;
; #pragma unroll
;     for (int j = 0; j < 4; ++j) { const int n = (lane >> 3) + 8 * j; const LAS float* s = scr + (8 * c) * 33 + n;
;         v4u o; o.x = pkbf(s[0 * 33], s[1 * 33]); o.y = pkbf(s[2 * 33], s[3 * 33]); o.z = pkbf(s[4 * 33], s[5 * 33]); o.w = pkbf(s[6 * 33], s[7 * 33]);
;         *(v4u*)(WT + (size_t)(n0 + n) * K + k0 + 8 * c) = o; }
	ds_write_b32 v36, v101 offset:792
	s_waitcnt vmcnt(27)
	ds_write_b32 v36, v102 offset:1056
	s_waitcnt vmcnt(26)
	ds_write_b32 v36, v103 offset:1320
	s_waitcnt vmcnt(25)
	ds_write_b32 v36, v104 offset:1584
	s_waitcnt vmcnt(24)
	ds_write_b32 v36, v105 offset:1848
	s_waitcnt vmcnt(23)
	ds_write_b32 v36, v106 offset:2112
	s_waitcnt vmcnt(22)
	ds_write_b32 v36, v107 offset:2376
	s_waitcnt vmcnt(21)
	ds_write_b32 v36, v108 offset:2640
	s_waitcnt vmcnt(20)
	ds_write_b32 v36, v109 offset:2904
	s_waitcnt vmcnt(19)
	ds_write_b32 v36, v110 offset:3168
	s_waitcnt vmcnt(18)
	ds_write_b32 v36, v111 offset:3432
	s_waitcnt vmcnt(17)
	ds_write_b32 v36, v112 offset:3696
	s_waitcnt vmcnt(16)
	ds_write_b32 v36, v113 offset:3960
	s_waitcnt vmcnt(15)
	ds_write_b32 v36, v114 offset:4224
	s_waitcnt vmcnt(14)
	ds_write_b32 v36, v115 offset:4488
	s_waitcnt vmcnt(13)
	ds_write_b32 v36, v116 offset:4752
	s_waitcnt vmcnt(12)
	ds_write_b32 v36, v117 offset:5016
	s_waitcnt vmcnt(11)
	ds_write_b32 v36, v118 offset:5280
	s_waitcnt vmcnt(10)
	ds_write_b32 v36, v119 offset:5544
	s_waitcnt vmcnt(9)
	ds_write_b32 v36, v120 offset:5808
	s_waitcnt vmcnt(8)
	ds_write_b32 v36, v121 offset:6072
	s_waitcnt vmcnt(7)
	ds_write_b32 v36, v204 offset:6336
	s_waitcnt vmcnt(6)
	ds_write_b32 v36, v205 offset:6600
	s_waitcnt vmcnt(5)
	ds_write_b32 v36, v206 offset:6864
	s_waitcnt vmcnt(4)
	ds_write_b32 v36, v207 offset:7128
	s_waitcnt vmcnt(3)
	ds_write_b32 v36, v208 offset:7392
	s_waitcnt vmcnt(2)
	ds_write_b32 v36, v209 offset:7656
	s_waitcnt vmcnt(1)
	ds_write_b32 v36, v210 offset:7920
	s_waitcnt vmcnt(0)
	ds_write_b32 v36, v211 offset:8184
	s_waitcnt lgkmcnt(0)
	ds_read2_b32 v[98:99], v37 offset0:0 offset1:33
	ds_read2_b32 v[100:101], v37 offset0:66 offset1:99
	ds_read2_b32 v[102:103], v37 offset0:132 offset1:165
	ds_read2_b32 v[104:105], v37 offset0:198 offset1:231
	ds_read2_b32 v[106:107], v37 offset0:8 offset1:41
	ds_read2_b32 v[108:109], v37 offset0:74 offset1:107
	ds_read2_b32 v[110:111], v37 offset0:140 offset1:173
	ds_read2_b32 v[112:113], v37 offset0:206 offset1:239
	ds_read2_b32 v[114:115], v37 offset0:16 offset1:49
	ds_read2_b32 v[116:117], v37 offset0:82 offset1:115
	ds_read2_b32 v[118:119], v37 offset0:148 offset1:181
	ds_read2_b32 v[120:121], v37 offset0:214 offset1:247
	ds_read2_b32 v[204:205], v37 offset0:24 offset1:57
	ds_read2_b32 v[206:207], v37 offset0:90 offset1:123
	ds_read2_b32 v[208:209], v37 offset0:156 offset1:189
	ds_read2_b32 v[210:211], v37 offset0:222 offset1:255
	s_waitcnt lgkmcnt(12)
	v_mul_f32_e32 v98, v98, v222
	v_mul_f32_e32 v99, v99, v223
	v_mul_f32_e32 v100, v100, v224
	v_mul_f32_e32 v101, v101, v225
	v_mul_f32_e32 v102, v102, v226
	v_mul_f32_e32 v103, v103, v227
	v_mul_f32_e32 v104, v104, v228
	v_mul_f32_e32 v105, v105, v229
	v_cvt_pk_bf16_f32 v244, v98, v99
	v_cvt_pk_bf16_f32 v245, v100, v101
	v_cvt_pk_bf16_f32 v246, v102, v103
	v_cvt_pk_bf16_f32 v247, v104, v105
	global_store_dwordx4 v40, v[244:247], s[22:23]
	v_add_u32_e32 v40, s45, v40
	s_waitcnt lgkmcnt(8)
	v_mul_f32_e32 v106, v106, v222
	v_mul_f32_e32 v107, v107, v223
	v_mul_f32_e32 v108, v108, v224
	v_mul_f32_e32 v109, v109, v225
	v_mul_f32_e32 v110, v110, v226
	v_mul_f32_e32 v111, v111, v227
	v_mul_f32_e32 v112, v112, v228
	v_mul_f32_e32 v113, v113, v229
	v_cvt_pk_bf16_f32 v230, v106, v107
	v_cvt_pk_bf16_f32 v231, v108, v109
	v_cvt_pk_bf16_f32 v232, v110, v111
	v_cvt_pk_bf16_f32 v233, v112, v113
	global_store_dwordx4 v40, v[230:233], s[22:23]
	v_add_u32_e32 v40, s45, v40
	s_waitcnt lgkmcnt(4)
	v_mul_f32_e32 v114, v114, v222
	v_mul_f32_e32 v115, v115, v223
	v_mul_f32_e32 v116, v116, v224
	v_mul_f32_e32 v117, v117, v225
	v_mul_f32_e32 v118, v118, v226
	v_mul_f32_e32 v119, v119, v227
	v_mul_f32_e32 v120, v120, v228
	v_mul_f32_e32 v121, v121, v229
	v_cvt_pk_bf16_f32 v244, v114, v115
	v_cvt_pk_bf16_f32 v245, v116, v117
	v_cvt_pk_bf16_f32 v246, v118, v119
	v_cvt_pk_bf16_f32 v247, v120, v121
	global_store_dwordx4 v40, v[244:247], s[22:23]
	v_add_u32_e32 v40, s45, v40
	s_waitcnt lgkmcnt(0)
	v_mul_f32_e32 v204, v204, v222
	v_mul_f32_e32 v205, v205, v223
	v_mul_f32_e32 v206, v206, v224
	v_mul_f32_e32 v207, v207, v225
	v_mul_f32_e32 v208, v208, v226
	v_mul_f32_e32 v209, v209, v227
	v_mul_f32_e32 v210, v210, v228
	v_mul_f32_e32 v211, v211, v229
	v_cvt_pk_bf16_f32 v230, v204, v205
	v_cvt_pk_bf16_f32 v231, v206, v207
	v_cvt_pk_bf16_f32 v232, v208, v209
	v_cvt_pk_bf16_f32 v233, v210, v211
	global_store_dwordx4 v40, v[230:233], s[22:23]
	s_add_i32 s30, s30, 0x400
	s_cmp_lt_u32 s30, 0x2000
	s_cbranch_scc1 .Ldcv_item
	s_add_i32 s17, s17, 1
	s_cmp_lt_u32 s17, 2
	s_cbranch_scc1 .Ldcv_matrix
	s_waitcnt vmcnt(0) lgkmcnt(0)
